# closed-form next-unit index in the P8 and P9 unit headers (fixed launch geometry: same row panel, column tile +4)
# speedup vs baseline: 1.0050x; 1.0023x over previous
;     __host__ __device__ bool next(int i, Unit& u) const { const int L = i * G + c; if (L >= n) return false; u.pm = L; u.pn = L >> 2; return true; }
;     __host__ __device__ bool next(int i, Unit& u) const {
;         const long L = (long)i * G + c; if (L >= nwg) return false;
;         int wgid = (int)L; { const int q = nwg / NXCD, r = nwg % NXCD, xcd = wgid % NXCD, off = wgid / NXCD; wgid = (xcd < r ? xcd * (q + 1) : r * (q + 1) + (xcd - r) * q) + off; }
;         const int nig = WGM * nN, gid = wgid / nig, fm = gid * WGM, gsz = (nM - fm) < WGM ? (nM - fm) : WGM;
;         u.pm = fm + ((wgid % nig) % gsz); u.pn = (wgid % nig) / gsz; return true;
;     }
; template <class Epi, class Sched, bool ALIGN_EPI>
; __device__ __forceinline__ void gemm_phase(PG8_LAS unsigned char* lds, const Gemm g, const Sched& S, const Epi& E) {
;     ...
;         const bool has_next = S.next(ui + 1, nxt);
;         const size_t tail_ = has_next ? 0 : tailoff; const char* nA = (has_next ? (const char*)g.A + (size_t)nxt.pm * tstepA : cA) + (has_next ? 0 : tailoffA); const char* nB = (has_next ? (const char*)g.Bt + (size_t)nxt.pn * tstepB : cB) + tail_;
.LBB0_937:
	s_add_i32 s42, s42, 1
	s_mul_i32 s0, s42, s45
	s_mul_hi_u32 s1, s42, s33
	s_add_i32 s1, s1, s0
	s_mul_i32 s0, s42, s33
	s_add_u32 s0, s0, s74
	s_addc_u32 s1, s1, s3
	v_cmp_gt_i64_e32 vcc, s[0:1], v[144:145]
	v_cmp_lt_i64_e64 s[6:7], s[0:1], v[142:143]
	s_mov_b64 s[24:25], 0x2b00
	s_cbranch_vccnz .LBB0_943
	s_add_i32 s53, s56, 4
	s_mov_b32 s54, s55
	s_mov_b64 s[24:25], 0
